# prologue: FFT constant matrices generated in 2048-element slices by 32 workgroups (ids 128..159) instead of 64 trig evaluations per thread on one workgroup each
# speedup vs baseline: 1.0056x; 1.0056x over previous
; __device__ __forceinline__ unsigned f2bf(float f) { unsigned u = __builtin_bit_cast(unsigned, f); return (u + 0x7fffu + ((u >> 16) & 1u)) >> 16; }
; __device__ __forceinline__ void prologue(const Args& A, LAS unsigned char* lds, int vcu, int G, const int tid) {
;     ...
;     const int vf = vcu - (G - 3);
;     if (vf == 0 || vf == 1) {
;         bf16_t* Mx = (bf16_t*)(ws + (vf == 0 ? WS_M1 : WS_M2));
;         for (int i = tid; i < 256 * 128; i += 512) { const int r = i >> 7, kap = i & 127, part = kap >> 6, nn = kap & 63; float v = 0.f;
;             if (vf == 0) { if (r < 64) { const float ph = (float)((r * nn) & 63) * (1.0f / 32.0f); v = part == 0 ? cospif(ph) : -sinpif(ph); }
;                             else if (r >= 128 && r < 192) { const float ph = (float)(((r - 128) * nn) & 63) * (1.0f / 32.0f); v = part == 0 ? -sinpif(ph) : -cospif(ph); } }
;             else { if (r < 64) { const float ph = (float)((r * nn) & 63) * (1.0f / 32.0f); v = part == 0 ? cospif(ph) : sinpif(ph); } }
;             Mx[i] = (bf16_t)f2bf(v); }
;     } else if (vf == 2) {
;         f32x2* TW = (f32x2*)(ws + WS_TW);
;         for (int i = tid; i < 4096; i += 512) { const float ph = (float)i * (1.0f / 2048.0f); TW[i] = (f32x2){cospif(ph), sinpif(ph)}; }
.LBB0_21:
	s_add_u32 s64, s94, 0x1000
	s_addc_u32 s65, s95, 0
	s_lshl_b32 s96, s33, 3
	s_add_u32 s50, s94, 0x83c40
	s_addc_u32 s51, s95, 0
	v_writelane_b32 v254, s92, 40
	s_cmp_lt_i32 s2, 1
	s_cselect_b64 s[0:1], -1, 0
	v_writelane_b32 v254, s93, 41
	v_writelane_b32 v254, s94, 42
	s_cmp_gt_i32 s3, 0
	v_writelane_b32 v254, s95, 43
	s_cselect_b64 s[2:3], -1, 0
	v_writelane_b32 v254, s63, 44
	s_and_b64 s[30:31], s[0:1], s[2:3]
	v_writelane_b32 v254, s64, 45
	s_andn2_b64 vcc, exec, s[30:31]
	s_nop 0
	v_writelane_b32 v254, s65, 46
	s_cbranch_vccnz .LBB0_185
	s_add_i32 s0, s33, -3
	v_readlane_b32 s1, v254, 7
	s_sub_i32 s2, s1, s0
	s_sub_i32 s52, s1, 0x80
	s_and_b32 s3, s52, 15
	s_lshl_b32 s3, s3, 11
	s_cmp_lt_u32 s52, 32
	s_cselect_b64 s[0:1], -1, 0
	s_cselect_b32 s3, s3, 0
	s_cmp_lt_u32 s52, 16
	s_cselect_b64 s[18:19], 0, -1
	s_cselect_b64 s[52:53], -1, 0
	v_mov_b32_e32 v0, v200
	v_ashrrev_i32_e32 v18, 6, v0
	s_andn2_b64 vcc, exec, s[0:1]
	v_readfirstlane_b32 s17, v18
	v_add_u32_e32 v0, s3, v0
	s_addk_i32 s3, 0x800
	s_mov_b64 s[0:1], -1
	s_cbranch_vccz .LBB0_29
	s_cmp_lg_u32 s2, 2
	s_cbranch_scc1 .LBB0_28
	s_movk_i32 s0, 0x1000
	v_cmp_gt_i32_e32 vcc, s0, v0
	s_and_saveexec_b64 s[0:1], vcc
	s_cbranch_execz .LBB0_27
	v_ashrrev_i32_e32 v1, 31, v0
	v_lshl_add_u64 v[2:3], v[0:1], 3, s[94:95]
	s_mov_b64 s[2:3], 0xb0000
	v_lshl_add_u64 v[2:3], v[2:3], 0, s[2:3]
	s_mov_b64 s[2:3], 0
	s_mov_b32 s6, 0x7f800000
	v_mov_b32_e32 v1, 0xbf1f24be
	v_mov_b32_e32 v4, 0x3e642e9d
	s_movk_i32 s7, 0x1f8
	v_mov_b32_e32 v5, 0x7fc00000
	s_mov_b64 s[4:5], 0x1000
	s_movk_i32 s8, 0xdff
	v_mov_b32_e32 v6, v0

; __device__ __forceinline__ unsigned f2bf(float f) { unsigned u = __builtin_bit_cast(unsigned, f); return (u + 0x7fffu + ((u >> 16) & 1u)) >> 16; }
; __device__ __forceinline__ void prologue(const Args& A, LAS unsigned char* lds, int vcu, int G, const int tid) {
;     ...
;         bf16_t* Mx = (bf16_t*)(ws + (vf == 0 ? WS_M1 : WS_M2));
;         for (int i = tid; i < 256 * 128; i += 512) { const int r = i >> 7, kap = i & 127, part = kap >> 6, nn = kap & 63; float v = 0.f;
;             if (vf == 0) { if (r < 64) { const float ph = (float)((r * nn) & 63) * (1.0f / 32.0f); v = part == 0 ? cospif(ph) : -sinpif(ph); }
;                             else if (r >= 128 && r < 192) { const float ph = (float)(((r - 128) * nn) & 63) * (1.0f / 32.0f); v = part == 0 ? -sinpif(ph) : -cospif(ph); } }
;             else { if (r < 64) { const float ph = (float)((r * nn) & 63) * (1.0f / 32.0f); v = part == 0 ? cospif(ph) : sinpif(ph); } }
;             Mx[i] = (bf16_t)f2bf(v); }
.LBB0_29:
	v_writelane_b32 v254, s30, 47
	s_andn2_b64 vcc, exec, s[0:1]
	s_nop 0
	v_writelane_b32 v254, s31, 48
	v_writelane_b32 v254, s28, 49
	v_writelane_b32 v254, s50, 50
	s_nop 1
	v_writelane_b32 v254, s51, 51
	v_writelane_b32 v254, s96, 52
	s_nop 1
	v_writelane_b32 v254, s97, 53
	s_cbranch_vccnz .LBB0_63
	s_mov_b32 s0, s3
	v_cmp_gt_i32_e32 vcc, s0, v0
	s_and_saveexec_b64 s[20:21], vcc
	s_cbranch_execz .LBB0_62
	s_add_i32 s0, s3, 0xfffffe00
	v_max_i32_e32 v1, s0, v0
	s_and_b64 s[0:1], s[52:53], exec
	v_sub_u32_e32 v1, v1, v0
	s_mov_b32 s2, 0x90000
	v_add_u32_e32 v1, 0x1ff, v1
	s_movk_i32 s0, 0x5ff
	s_cselect_b32 s2, s2, 0xa0000
	v_cmp_lt_u32_e32 vcc, s0, v1
	s_mov_b64 s[0:1], -1
	v_mov_b32_e32 v2, v0
	s_and_saveexec_b64 s[6:7], vcc
	s_cbranch_execz .LBB0_35
	v_writelane_b32 v254, s6, 54
	v_lshrrev_b32_e32 v1, 9, v1
	v_add_u32_e32 v19, 1, v1
	v_writelane_b32 v254, s7, 55
	v_writelane_b32 v254, s20, 56
	v_add_u32_e32 v3, 0x600, v0
	v_add_u32_e32 v2, 0x400, v0
	v_writelane_b32 v254, s21, 57
	v_writelane_b32 v254, s18, 58
	s_mov_b32 s0, 0xbf1f24be
	s_add_u32 s56, s94, s2
	v_writelane_b32 v254, s19, 59
	v_writelane_b32 v254, s17, 60
	v_and_b32_e32 v20, 0xfffffc, v19
	v_add_u32_e32 v1, 0x200, v0
	v_mov_b64_e32 v[6:7], s[0:1]
	s_mov_b32 s0, 0x3e642e9d
	v_mov_b64_e32 v[4:5], v[2:3]
	v_writelane_b32 v254, s2, 62
	s_addc_u32 s57, s95, 0
	s_xor_b64 s[54:55], s[52:53], -1
	s_mov_b64 s[96:97], 0
	s_mov_b32 s47, 0x7f800000
	s_mov_b32 s46, 0x40234736
	s_mov_b32 s94, 0x3d4be544
	v_mov_b64_e32 v[8:9], s[0:1]
	s_mov_b32 s48, 0xbfaad1da
	s_mov_b32 s60, 0xc09de9e6
	s_brev_b32 s49, 1
	v_mov_b32_e32 v21, 0x7fc00000
	s_movk_i32 s61, 0x80
	v_mov_b32_e32 v22, 0xffc00000
	s_movk_i32 s95, 0x7fff
	v_mov_b32_e32 v23, v20
	v_mov_b64_e32 v[2:3], v[0:1]

; __device__ __forceinline__ void prologue(const Args& A, LAS unsigned char* lds, int vcu, int G, const int tid) {
;     ...
;     for (int it = vcu; it < 257; it += G) {
;         if (it < 128) {
;             LAS float* sc = (LAS float*)lds;
;             LAS float* red = (LAS float*)(lds + 5 * 1024 * 4);
;             for (int i = tid; i < 5 * 1024; i += 512) { const int r = i >> 10, k = i & 1023; const float cv = r < 4 ? A.in[I_C][r * 1024 + k] : A.in[I_CCTX][k]; sc[i] = cv / (1.0f + expf(-cv)); }
;             __syncthreads();
;             const int n0 = it * 72, c4 = tid % 18, kg = tid / 18;
;             f32x4 a0 = {0.f, 0.f, 0.f, 0.f}, a1 = a0, a2 = a0, a3 = a0, a4 = a0;
;             if (kg < 28) {
;                 const float* wp = A.in[I_WADA] + n0 + 4 * c4;
; #pragma unroll 8
;                 for (int kk = 0; kk < 37; ++kk) { const int k = kg + 28 * kk; if (k < 1024) { const f32x4 w = __builtin_nontemporal_load((const f32x4*)(wp + (size_t)k * MODLD));
;                     a0 += w * sc[k]; a1 += w * sc[1024 + k]; a2 += w * sc[2048 + k]; a3 += w * sc[3072 + k]; a4 += w * sc[4096 + k]; } }
;                 *(LAS f32x4*)(red + (0 * 28 + kg) * 72 + 4 * c4) = a0; *(LAS f32x4*)(red + (1 * 28 + kg) * 72 + 4 * c4) = a1; *(LAS f32x4*)(red + (2 * 28 + kg) * 72 + 4 * c4) = a2;
;                 *(LAS f32x4*)(red + (3 * 28 + kg) * 72 + 4 * c4) = a3; *(LAS f32x4*)(red + (4 * 28 + kg) * 72 + 4 * c4) = a4; }
;             __syncthreads();
;             if (tid < 360) { const int r = tid / 72, n = tid % 72; float s_ = A.in[I_BADA][n0 + n];
;                 for (int q = 0; q < 28; ++q) s_ += red[(r * 28 + q) * 72 + n];
;                 __hip_atomic_store((float*)(ws + WS_MOD) + r * MODLD + n0 + n, s_, __ATOMIC_RELAXED, __HIP_MEMORY_SCOPE_AGENT); }
;             wg_publish((unsigned*)(ws + WS_BAR) + 3856);
;             __syncthreads();
;         } else if (it < 192) {
;             const int item = it - 128, k0 = (item >> 2) * 64, g = item & 3;
;             LAS float* wt = (LAS float*)lds;
;             LAS float* tab = (LAS float*)(lds + 64 * 65 * 4);
;             for (int i = tid; i < 4096; i += 512) { const int kk = i >> 6, d = i & 63; wt[kk * 65 + d] = A.in[I_WIN][(size_t)(k0 + kk) * 2560 + 2304 + g * 64 + d]; }
;             if (tid < 64) tab[tid] = cospif((float)tid * (1.0f / 32.0f));
;             __syncthreads();
.LBB0_63:
	v_mov_b32_e32 v0, v200
	v_and_b32_e32 v46, 63, v0
	v_readlane_b32 s0, v254, 7
	s_cmpk_gt_i32 s0, 0x100
	v_lshlrev_b32_e32 v48, 2, v46
	s_cbranch_scc1 .LBB0_182
	s_movk_i32 s0, 0x4000
	v_cmp_gt_i32_e64 s[0:1], s0, v0
	s_lshl_b32 s93, s17, 13
	v_cvt_f32_i32_e32 v1, v0
	v_writelane_b32 v254, s0, 60
	v_mov_b32_e32 v7, 0xbf1f24be
	s_movk_i32 s62, 0x1f8
	v_writelane_b32 v254, s1, 61
	s_lshl_b32 s0, s17, 3
	s_ashr_i32 s1, s0, 31
	v_writelane_b32 v254, s0, 58
	v_mul_f32_e32 v1, 0x3d000000, v1
	v_mul_f32_e64 v2, |v1|, 0.5
	v_writelane_b32 v254, s1, 59
	v_fract_f32_e32 v3, v2
	v_readlane_b32 s8, v254, 40
	v_readlane_b32 s10, v254, 42
	v_readlane_b32 s11, v254, 43
	s_add_u32 s22, s10, 0x2780600
	s_addc_u32 s23, s11, 0
	s_cmp_eq_u32 s17, 0
	s_cselect_b64 s[0:1], -1, 0
	v_readlane_b32 s9, v254, 41
	v_writelane_b32 v254, s0, 56
	v_add_f32_e32 v3, v3, v3
	v_cmp_gt_f32_e64 s[2:3], |v1|, 1.0
	v_writelane_b32 v254, s1, 57
	s_mov_b32 s0, 0x7f800000
	v_cmp_neq_f32_e32 vcc, s0, v2
	v_mov_b32_e32 v47, 0x7fc00000
	s_movk_i32 s1, 0x100
	v_cndmask_b32_e32 v2, 0, v3, vcc
	v_cndmask_b32_e64 v2, |v1|, v2, s[2:3]
	v_add_f32_e32 v3, v2, v2
	v_rndne_f32_e32 v4, v3
	v_fmac_f32_e32 v2, -0.5, v4
	v_mul_f32_e32 v6, v2, v2
	v_fmac_f32_e32 v7, 0x3e75aa41, v6
	v_fmaak_f32 v7, v6, v7, 0x40234736
	v_fmaak_f32 v7, v6, v7, 0xc0a55e0e
	v_mul_f32_e32 v8, v2, v6
	v_mul_f32_e32 v7, v8, v7
	v_cvt_i32_f32_e32 v5, v4
	v_fmamk_f32 v2, v2, 0x40490fdb, v7
	v_mov_b32_e32 v7, 0x3e642e9d
	v_fmac_f32_e32 v7, 0x3d4be544, v6
	v_fmaak_f32 v7, v6, v7, 0xbfaad1da
	v_fmaak_f32 v7, v6, v7, 0x4081e0d3
	v_and_b32_e32 v4, 2, v5
	v_fmaak_f32 v7, v6, v7, 0xc09de9e6
	v_and_b32_e32 v5, 1, v5
	v_fma_f32 v6, v6, v7, 1.0
	v_cmp_eq_u32_e32 vcc, 0, v5
	v_mov_b32_e32 v3, 0
	s_mov_b64 s[2:3], 0x2680000
	v_cndmask_b32_e64 v2, -v2, v6, vcc
	v_cmp_eq_u32_e32 vcc, 0, v4
	v_mov_b32_e32 v49, v3
	s_movk_i32 s66, 0x1ff
	v_cndmask_b32_e64 v2, -v2, v2, vcc
	v_cmp_class_f32_e64 vcc, v1, s62
	v_lshlrev_b32_e32 v1, 4, v18
	v_and_b32_e32 v84, 48, v1
	v_cndmask_b32_e32 v51, v47, v2, vcc
	v_cmp_gt_u32_e32 vcc, s1, v0
	s_movk_i32 s1, 0x1400
	v_mov_b32_e32 v1, 0x100
	v_cmp_gt_i32_e64 s[48:49], s1, v0
	s_mov_b32 s1, 0x38e38e39
	v_cndmask_b32_e32 v85, 48, v1, vcc
	v_lshlrev_b32_e32 v2, 1, v46
	v_mul_hi_i32 v1, v0, s1
	v_lshl_add_u64 v[4:5], s[10:11], 0, v[2:3]
	v_ashrrev_i32_e32 v2, 2, v1
	v_lshrrev_b32_e32 v6, 31, v1
	v_add_u32_e32 v2, v2, v6
	s_movk_i32 s1, 0x120
	v_mul_lo_u32 v8, v2, s1
	s_movk_i32 s1, 0x168
	v_ashrrev_i32_e32 v1, 4, v1
	v_lshl_add_u64 v[52:53], v[4:5], 0, s[2:3]
	v_mul_lo_u32 v4, v2, 18
	v_cmp_gt_i32_e64 s[26:27], s1, v0
	v_add_u32_e32 v1, v1, v6
	s_movk_i32 s1, 0x48
	v_sub_u32_e32 v7, v0, v4
	v_mul_lo_u32 v6, v1, s1
	s_movk_i32 s1, 0x2400
	v_lshlrev_b32_e32 v4, 2, v7
	v_lshlrev_b32_e32 v7, 4, v7
	v_sub_u32_e32 v54, v0, v6
	v_mul_lo_u32 v6, v1, s1
	v_readlane_b32 s2, v254, 45
	v_add3_u32 v88, 0, v8, v7
	v_ashrrev_i32_e32 v7, 31, v6
	v_readlane_b32 s3, v254, 46
	v_ashrrev_i32_e32 v55, 31, v54
	s_mov_b32 s1, 0x3f2aaaab
	v_lshl_add_u64 v[6:7], v[6:7], 2, s[2:3]
	v_lshl_add_u64 v[56:57], v[54:55], 2, v[6:7]
	v_and_b32_e32 v6, 15, v0
	v_cvt_f32_ubyte0_e32 v6, v6
	v_mul_f32_e32 v21, 0xbd800000, v6
	v_mov_b32_e32 v6, 0x461c4000
	v_cmp_eq_f32_e32 vcc, 0, v21
	s_movk_i32 s2, 0x204
	s_mov_b32 s3, 0x3fb8aa3b
	v_cndmask_b32_e64 v16, v6, 1.0, vcc
	v_frexp_mant_f32_e32 v6, v16
	v_cmp_gt_f32_e64 s[6:7], s1, v6
	s_mov_b32 s1, 0x3f317218
	v_mov_b32_e32 v55, 0x7f800000
	v_cndmask_b32_e64 v7, 1.0, 2.0, s[6:7]
	v_mul_f32_e32 v6, v6, v7
	v_add_f32_e32 v9, 1.0, v6
	v_rcp_f32_e32 v14, v9
	v_add_f32_e32 v7, -1.0, v9
	v_sub_f32_e32 v11, v6, v7
	v_add_f32_e32 v7, -1.0, v6
	v_mul_f32_e32 v15, v7, v14
	v_mul_f32_e32 v8, v9, v15
	v_fma_f32 v10, v15, v9, -v8
	v_fmac_f32_e32 v10, v15, v11
	v_add_f32_e32 v6, v8, v10
	v_sub_f32_e32 v9, v7, v6
	v_pk_add_f32 v[12:13], v[6:7], v[8:9] neg_lo:[0,1] neg_hi:[0,1]
	v_mov_b32_e32 v11, v6
	v_pk_add_f32 v[6:7], v[12:13], v[10:11] neg_lo:[0,1] neg_hi:[0,1]
	v_mov_b32_e32 v10, 0x3e91f4c4
	v_add_f32_e32 v6, v6, v7
	v_add_f32_e32 v6, v9, v6
	v_mul_f32_e32 v7, v14, v6
	v_add_f32_e32 v6, v15, v7
	v_sub_f32_e32 v8, v6, v15
	v_sub_f32_e32 v17, v7, v8
	v_mul_f32_e32 v7, v6, v6
	v_fma_f32 v9, v6, v6, -v7
	v_add_f32_e32 v8, v17, v17
	v_fmac_f32_e32 v9, v6, v8
	v_add_f32_e32 v8, v7, v9
	v_fmac_f32_e32 v10, 0x3e76c4e1, v8
	v_fmaak_f32 v10, v8, v10, 0x3ecccdef
	v_sub_f32_e32 v7, v8, v7
	v_sub_f32_e32 v18, v9, v7
	v_mul_f32_e32 v7, v8, v10
	v_fma_f32 v9, v8, v10, -v7
	v_fmac_f32_e32 v9, v18, v10
	v_add_f32_e32 v10, v7, v9
	v_add_f32_e32 v11, 0x3f2aaaaa, v10
	v_sub_f32_e32 v7, v10, v7
	v_sub_f32_e32 v7, v9, v7
	v_add_f32_e32 v9, 0xbf2aaaaa, v11
	v_add_f32_e32 v7, 0x31739010, v7
	v_sub_f32_e32 v9, v10, v9
	v_pk_mul_f32 v[12:13], v[6:7], v[8:9]
	v_pk_add_f32 v[14:15], v[6:7], v[8:9]
	v_fma_f32 v10, v8, v6, -v12
	v_fmac_f32_e32 v10, v8, v17
	v_mov_b32_e32 v13, v15
	v_fmac_f32_e32 v10, v18, v6
	v_pk_add_f32 v[8:9], v[12:13], v[10:11]
	v_ldexp_f32 v18, v17, 1
	v_sub_f32_e32 v7, v8, v12
	v_sub_f32_e32 v7, v10, v7
	v_sub_f32_e32 v10, v11, v9
	v_add_f32_e32 v13, v15, v10
	v_pk_mul_f32 v[10:11], v[8:9], v[8:9] op_sel:[0,1] op_sel_hi:[1,0]
	v_cvt_f64_f32_e32 v[14:15], v16
	v_frexp_exp_i32_f64_e32 v11, v[14:15]
	v_subbrev_co_u32_e64 v11, s[6:7], 0, v11, s[6:7]
	v_cvt_f32_i32_e32 v11, v11
	v_fma_f32 v12, v8, v9, -v10
	v_fmac_f32_e32 v12, v8, v13
	v_fmac_f32_e32 v12, v7, v9
	v_mul_f32_e32 v8, 0x3f317218, v11
	v_fma_f32 v7, v11, s1, -v8
	v_fmamk_f32 v14, v11, 0xb102e308, v7
	v_ldexp_f32 v15, v6, 1
	v_add_f32_e32 v9, v10, v12
	v_pk_add_f32 v[6:7], v[8:9], v[14:15]
	v_mov_b32_e32 v16, v9
	v_mov_b32_e32 v17, v7
; #define LAS __attribute__((address_space(3)))
; __device__ __forceinline__ void prologue(const Args& A, LAS unsigned char* lds, int vcu, int G, const int tid) {
;     ...
;             for (int i = tid; i < 5 * 1024; i += 512) { const int r = i >> 10, k = i & 1023; const float cv = r < 4 ? A.in[I_C][r * 1024 + k] : A.in[I_CCTX][k]; sc[i] = cv / (1.0f + expf(-cv)); }
;             __syncthreads();
;             const int n0 = it * 72, c4 = tid % 18, kg = tid / 18;
;             f32x4 a0 = {0.f, 0.f, 0.f, 0.f}, a1 = a0, a2 = a0, a3 = a0, a4 = a0;
;             if (kg < 28) {
;                 const float* wp = A.in[I_WADA] + n0 + 4 * c4;
; #pragma unroll 8
;                 for (int kk = 0; kk < 37; ++kk) { const int k = kg + 28 * kk; if (k < 1024) { const f32x4 w = __builtin_nontemporal_load((const f32x4*)(wp + (size_t)k * MODLD));
;                     a0 += w * sc[k]; a1 += w * sc[1024 + k]; a2 += w * sc[2048 + k]; a3 += w * sc[3072 + k]; a4 += w * sc[4096 + k]; } }
;                 *(LAS f32x4*)(red + (0 * 28 + kg) * 72 + 4 * c4) = a0; *(LAS f32x4*)(red + (1 * 28 + kg) * 72 + 4 * c4) = a1; *(LAS f32x4*)(red + (2 * 28 + kg) * 72 + 4 * c4) = a2;
;                 *(LAS f32x4*)(red + (3 * 28 + kg) * 72 + 4 * c4) = a3; *(LAS f32x4*)(red + (4 * 28 + kg) * 72 + 4 * c4) = a4; }
;             __syncthreads();
;             if (tid < 360) { const int r = tid / 72, n = tid % 72; float s_ = A.in[I_BADA][n0 + n];
;                 for (int q = 0; q < 28; ++q) s_ += red[(r * 28 + q) * 72 + n];
;                 __hip_atomic_store((float*)(ws + WS_MOD) + r * MODLD + n0 + n, s_, __ATOMIC_RELAXED, __HIP_MEMORY_SCOPE_AGENT); }
;             wg_publish((unsigned*)(ws + WS_BAR) + 3856);
;             __syncthreads();
;         } else if (it < 192) {
;             const int item = it - 128, k0 = (item >> 2) * 64, g = item & 3;
;             LAS float* wt = (LAS float*)lds;
;             LAS float* tab = (LAS float*)(lds + 64 * 65 * 4);
;             for (int i = tid; i < 4096; i += 512) { const int kk = i >> 6, d = i & 63; wt[kk * 65 + d] = A.in[I_WIN][(size_t)(k0 + kk) * 2560 + 2304 + g * 64 + d]; }
;             if (tid < 64) tab[tid] = cospif((float)tid * (1.0f / 32.0f));
;             __syncthreads();
;             const int kk = tid & 63, grp = tid >> 6;
;             bf16_t* WF = (bf16_t*)(ws + WS_WF);
;             for (int jj = 0; jj < 16; ++jj) {
	v_mov_b32_e32 v11, v15
	v_pk_add_f32 v[10:11], v[16:17], v[10:11] neg_lo:[0,1] neg_hi:[0,1]
	v_mov_b32_e32 v13, v9
	v_pk_add_f32 v[10:11], v[12:13], v[10:11] neg_lo:[0,1] neg_hi:[0,1]
	v_mov_b32_e32 v15, v6
	v_add_f32_e32 v9, v18, v10
	v_add_f32_e32 v9, v9, v11
	v_pk_add_f32 v[10:11], v[6:7], v[8:9] neg_lo:[0,1] neg_hi:[0,1]
	v_pk_add_f32 v[12:13], v[6:7], v[8:9]
	v_mov_b32_e32 v8, v9
	v_mov_b32_e32 v11, v13
	v_pk_add_f32 v[16:17], v[14:15], v[10:11] neg_lo:[0,1] neg_hi:[0,1]
	v_pk_add_f32 v[10:11], v[14:15], v[10:11]
	v_mov_b32_e32 v9, v6
	v_pk_add_f32 v[14:15], v[10:11], v[6:7] op_sel:[1,0] op_sel_hi:[0,1] neg_lo:[0,1] neg_hi:[0,1]
	v_pk_add_f32 v[18:19], v[12:13], v[14:15] op_sel_hi:[1,0] neg_lo:[0,1] neg_hi:[0,1]
	v_mov_b32_e32 v12, v13
	v_mov_b32_e32 v13, v11
	v_pk_mov_b32 v[14:15], v[6:7], v[14:15] op_sel:[1,0]
	v_mov_b32_e32 v18, v16
	v_pk_add_f32 v[12:13], v[12:13], v[14:15] neg_lo:[0,1] neg_hi:[0,1]
	v_mov_b32_e32 v17, v11
	v_pk_add_f32 v[6:7], v[8:9], v[12:13] neg_lo:[0,1] neg_hi:[0,1]
	s_mov_b32 s1, 0x42b17218
	v_pk_add_f32 v[8:9], v[18:19], v[6:7]
	v_ashrrev_i32_e32 v5, 31, v4
	v_pk_add_f32 v[12:13], v[8:9], v[8:9] op_sel:[0,1] op_sel_hi:[1,0]
	v_lshlrev_b64 v[4:5], 2, v[4:5]
	v_pk_add_f32 v[10:11], v[10:11], v[12:13] op_sel:[1,0] op_sel_hi:[0,1]
	v_mov_b32_e32 v9, v10
	v_pk_add_f32 v[14:15], v[8:9], v[16:17] neg_lo:[0,1] neg_hi:[0,1]
	v_mov_b32_e32 v7, v12
	v_sub_f32_e32 v8, v8, v14
	v_pk_add_f32 v[6:7], v[6:7], v[14:15] neg_lo:[0,1] neg_hi:[0,1]
	v_sub_f32_e32 v8, v16, v8
	v_add_f32_e32 v6, v6, v8
	v_add_f32_e32 v6, v6, v7
	v_add_f32_e32 v7, v10, v6
	v_sub_f32_e32 v8, v7, v10
	v_sub_f32_e32 v6, v6, v8
	v_mul_f32_e32 v8, v21, v7
	v_fma_f32 v7, v21, v7, -v8
	v_fmac_f32_e32 v7, v21, v6
	v_add_f32_e32 v6, v8, v7
	v_cmp_class_f32_e64 s[6:7], v8, s2
	v_sub_f32_e32 v9, v6, v8
	v_sub_f32_e32 v7, v7, v9
	v_cndmask_b32_e64 v6, v6, v8, s[6:7]
	v_mov_b32_e32 v8, 0x37000000
	v_cmp_eq_f32_e64 s[6:7], s1, v6
	v_readlane_b32 s16, v254, 7
	v_add_u32_e32 v105, 0xc4, v2
	v_cndmask_b32_e64 v8, 0, v8, s[6:7]
	v_sub_f32_e32 v9, v6, v8
	v_mul_f32_e32 v10, 0x3fb8aa3b, v9
	v_fma_f32 v11, v9, s3, -v10
	v_rndne_f32_e32 v12, v10
	v_fmac_f32_e32 v11, 0x32a5705f, v9
	v_sub_f32_e32 v10, v10, v12
	v_add_f32_e32 v10, v10, v11
	v_exp_f32_e32 v10, v10
	v_cvt_i32_f32_e32 v11, v12
	v_cmp_neq_f32_e64 s[6:7], |v6|, s0
	s_mov_b32 s0, 0xc2ce8ed0
	v_lshl_add_u32 v106, v2, 2, 0
	v_cndmask_b32_e64 v6, 0, v7, s[6:7]
	v_ldexp_f32 v7, v10, v11
	v_cmp_ngt_f32_e64 s[6:7], s0, v9
	v_add_f32_e32 v6, v8, v6
	v_lshlrev_b32_e32 v82, 2, v0
	v_cndmask_b32_e64 v7, 0, v7, s[6:7]
	v_cmp_nlt_f32_e64 s[6:7], s1, v9
	v_cmp_neq_f32_e64 s[0:1], v21, |v21|
	v_add_u32_e32 v50, 0, v48
	v_cndmask_b32_e64 v7, v55, v7, s[6:7]
	v_fma_f32 v6, v7, v6, v7
	v_cmp_class_f32_e64 s[6:7], v7, s2
	s_movk_i32 s60, 0x400
	s_movk_i32 s61, 0x1000
	v_cndmask_b32_e64 v6, v6, v7, s[6:7]
	v_cndmask_b32_e64 v7, v55, 0, s[0:1]
	v_cndmask_b32_e64 v7, v7, 1.0, vcc
	v_cmp_class_f32_e64 s[0:1], v21, s2
	v_add_u32_e32 v83, 0, v82
	v_lshl_add_u32 v20, v54, 2, 0
	v_cndmask_b32_e64 v89, |v6|, v7, s[0:1]
	v_max_i32_e32 v6, 0xe00, v0
	v_max_i32_e32 v7, 0x3e00, v0
	v_sub_u32_e32 v6, v6, v0
	v_sub_u32_e32 v7, v7, v0
	v_add_u32_e32 v11, 0x1ff, v6
	v_add_u32_e32 v13, 0x1ff, v7
	v_lshrrev_b32_e32 v6, 9, v11
	v_lshrrev_b32_e32 v7, 9, v13
	v_add_u32_e32 v15, -1, v7
	v_add_u32_e32 v16, -1, v6
	v_add_u32_e32 v12, 1, v6
	v_add_u32_e32 v14, 1, v7
	v_lshrrev_b32_e32 v7, 1, v15
	v_lshrrev_b32_e32 v6, 1, v16
	v_add_u32_e32 v7, 1, v7
	v_add_u32_e32 v6, 1, v6
	v_and_b32_e32 v90, 3, v7
	v_and_b32_e32 v91, -4, v7
	v_and_b32_e32 v92, 7, v7
	v_and_b32_e32 v93, -8, v7
	v_and_b32_e32 v95, -2, v6
	v_ashrrev_i32_e32 v7, 31, v0
	v_mov_b32_e32 v6, v0
	s_movk_i32 s0, 0x1f80
	v_lshlrev_b64 v[58:59], 2, v[6:7]
	v_mul_lo_u32 v8, v1, s0
	v_lshl_add_u64 v[6:7], s[10:11], 0, v[58:59]
	s_mov_b64 s[0:1], 0x40000
	v_lshl_add_u64 v[60:61], v[6:7], 0, s[0:1]
	s_mov_b32 s0, 0x9000
	v_mad_i64_i32 v[4:5], s[0:1], v2, s0, v[4:5]
	v_readlane_b32 s0, v254, 24
	v_readlane_b32 s1, v254, 25
	v_readlane_b32 s2, v254, 26
	v_readlane_b32 s3, v254, 27
	v_readlane_b32 s4, v254, 28
	v_readlane_b32 s5, v254, 29
	v_readlane_b32 s6, v254, 30
	v_readlane_b32 s7, v254, 31
	v_readlane_b32 s8, v254, 32
	v_readlane_b32 s9, v254, 33
	v_readlane_b32 s10, v254, 34
	v_readlane_b32 s11, v254, 35
	v_readlane_b32 s12, v254, 36
	v_readlane_b32 s13, v254, 37
	v_readlane_b32 s14, v254, 38
	v_readlane_b32 s15, v254, 39
	v_lshl_add_u64 v[64:65], s[4:5], 0, v[48:49]
	v_readlane_b32 s0, v254, 8
	v_readlane_b32 s1, v254, 9
	v_readlane_b32 s2, v254, 10
	v_readlane_b32 s3, v254, 11
	v_readlane_b32 s4, v254, 12
	v_readlane_b32 s5, v254, 13
	v_readlane_b32 s6, v254, 14
	v_readlane_b32 s7, v254, 15
	v_readlane_b32 s8, v254, 16
	v_readlane_b32 s9, v254, 17
	v_readlane_b32 s10, v254, 18
	v_readlane_b32 s11, v254, 19
	v_readlane_b32 s12, v254, 20
	v_readlane_b32 s13, v254, 21
	v_readlane_b32 s14, v254, 22
	v_readlane_b32 s15, v254, 23
	v_lshl_add_u64 v[66:67], s[8:9], 0, v[48:49]
	v_readlane_b32 s0, v254, 8
	v_readlane_b32 s1, v254, 9
	v_readlane_b32 s2, v254, 10
	v_readlane_b32 s3, v254, 11
	v_readlane_b32 s4, v254, 12
	v_readlane_b32 s5, v254, 13
	v_readlane_b32 s6, v254, 14
; __device__ __forceinline__ void prologue(const Args& A, LAS unsigned char* lds, int vcu, int G, const int tid) {
;     ...
;     for (int it = vcu; it < 257; it += G) {
;         if (it < 128) {
;             LAS float* sc = (LAS float*)lds;
;             LAS float* red = (LAS float*)(lds + 5 * 1024 * 4);
;             for (int i = tid; i < 5 * 1024; i += 512) { const int r = i >> 10, k = i & 1023; const float cv = r < 4 ? A.in[I_C][r * 1024 + k] : A.in[I_CCTX][k]; sc[i] = cv / (1.0f + expf(-cv)); }
;             __syncthreads();
;             const int n0 = it * 72, c4 = tid % 18, kg = tid / 18;
;             f32x4 a0 = {0.f, 0.f, 0.f, 0.f}, a1 = a0, a2 = a0, a3 = a0, a4 = a0;
;             if (kg < 28) {
;                 const float* wp = A.in[I_WADA] + n0 + 4 * c4;
; #pragma unroll 8
;                 for (int kk = 0; kk < 37; ++kk) { const int k = kg + 28 * kk; if (k < 1024) { const f32x4 w = __builtin_nontemporal_load((const f32x4*)(wp + (size_t)k * MODLD));
;                     a0 += w * sc[k]; a1 += w * sc[1024 + k]; a2 += w * sc[2048 + k]; a3 += w * sc[3072 + k]; a4 += w * sc[4096 + k]; } }
;                 *(LAS f32x4*)(red + (0 * 28 + kg) * 72 + 4 * c4) = a0; *(LAS f32x4*)(red + (1 * 28 + kg) * 72 + 4 * c4) = a1; *(LAS f32x4*)(red + (2 * 28 + kg) * 72 + 4 * c4) = a2;
;                 *(LAS f32x4*)(red + (3 * 28 + kg) * 72 + 4 * c4) = a3; *(LAS f32x4*)(red + (4 * 28 + kg) * 72 + 4 * c4) = a4; }
;             __syncthreads();
;             if (tid < 360) { const int r = tid / 72, n = tid % 72; float s_ = A.in[I_BADA][n0 + n];
;                 for (int q = 0; q < 28; ++q) s_ += red[(r * 28 + q) * 72 + n];
;                 __hip_atomic_store((float*)(ws + WS_MOD) + r * MODLD + n0 + n, s_, __ATOMIC_RELAXED, __HIP_MEMORY_SCOPE_AGENT); }
;             wg_publish((unsigned*)(ws + WS_BAR) + 3856);
;             __syncthreads();
;         } else if (it < 192) {
;             const int item = it - 128, k0 = (item >> 2) * 64, g = item & 3;
;             LAS float* wt = (LAS float*)lds;
;             LAS float* tab = (LAS float*)(lds + 64 * 65 * 4);
;             for (int i = tid; i < 4096; i += 512) { const int kk = i >> 6, d = i & 63; wt[kk * 65 + d] = A.in[I_WIN][(size_t)(k0 + kk) * 2560 + 2304 + g * 64 + d]; }
;             if (tid < 64) tab[tid] = cospif((float)tid * (1.0f / 32.0f));
;             __syncthreads();
	v_readlane_b32 s7, v254, 15
	v_readlane_b32 s8, v254, 16
	v_readlane_b32 s9, v254, 17
	v_readlane_b32 s10, v254, 18
	v_readlane_b32 s11, v254, 19
	v_readlane_b32 s12, v254, 20
	v_readlane_b32 s13, v254, 21
	v_readlane_b32 s14, v254, 22
	v_readlane_b32 s15, v254, 23
	v_lshl_add_u64 v[68:69], s[10:11], 0, v[48:49]
	v_readlane_b32 s0, v254, 8
	v_readlane_b32 s1, v254, 9
	v_readlane_b32 s2, v254, 10
	v_readlane_b32 s3, v254, 11
	v_readlane_b32 s4, v254, 12
	v_readlane_b32 s5, v254, 13
	v_readlane_b32 s6, v254, 14
	v_readlane_b32 s7, v254, 15
	v_readlane_b32 s8, v254, 16
	v_readlane_b32 s9, v254, 17
	v_readlane_b32 s10, v254, 18
	v_readlane_b32 s11, v254, 19
	v_readlane_b32 s12, v254, 20
	v_readlane_b32 s13, v254, 21
	v_readlane_b32 s14, v254, 22
	v_readlane_b32 s15, v254, 23
	v_lshl_add_u64 v[70:71], s[12:13], 0, v[48:49]
	v_readlane_b32 s0, v254, 8
	v_readlane_b32 s2, v254, 10
	v_readlane_b32 s3, v254, 11
	v_cmp_eq_u32_e64 s[2:3], 0, v46
	v_readlane_b32 s1, v254, 9
	v_readlane_b32 s4, v254, 12
	v_writelane_b32 v255, s2, 0
	v_readlane_b32 s5, v254, 13
	v_readlane_b32 s6, v254, 14
	v_writelane_b32 v255, s3, 1
	v_cmp_lt_u32_e64 s[2:3], s66, v13
	v_readlane_b32 s7, v254, 15
	v_readlane_b32 s8, v254, 16
	v_readlane_b32 s9, v254, 17
	v_readlane_b32 s10, v254, 18
	v_readlane_b32 s11, v254, 19
	v_readlane_b32 s12, v254, 20
	v_readlane_b32 s13, v254, 21
	v_readlane_b32 s14, v254, 22
	v_readlane_b32 s15, v254, 23
	v_writelane_b32 v254, s2, 62
	v_and_b32_e32 v19, 0xfffffe, v14
	v_max_i32_e32 v1, 0x1200, v0
	v_writelane_b32 v254, s3, 63
	v_cmp_lt_u32_e64 s[2:3], 5, v15
	v_and_b32_e32 v22, 2, v16
	v_sub_u32_e32 v1, v1, v0
	v_writelane_b32 v255, s2, 2
	v_add_u32_e32 v9, 0x1ff, v1
	v_and_b32_e32 v21, 0xfffffe, v12
	v_writelane_b32 v255, s3, 3
	v_cmp_ne_u32_e64 s[2:3], 0, v90
	v_lshrrev_b32_e32 v1, 9, v9
	v_add_u32_e32 v17, -1, v1
	v_writelane_b32 v255, s2, 4
	v_and_b32_e32 v2, 2, v17
	v_add_u32_e32 v10, 1, v1
	v_writelane_b32 v255, s3, 5
	v_cmp_ne_u32_e64 s[2:3], v14, v19
	v_and_b32_e32 v23, 0xfffffe, v10
	v_lshrrev_b32_e32 v1, 1, v17
	v_writelane_b32 v255, s2, 6
	v_add_u32_e32 v18, 1, v1
	s_lshl_b32 s67, s16, 6
	v_writelane_b32 v255, s3, 7
	v_cmp_lt_u32_e64 s[2:3], 13, v15
	v_bfe_u32 v6, v0, 6, 2
	v_lshl_add_u64 v[62:63], s[84:85], 0, v[4:5]
	v_writelane_b32 v255, s2, 8
	v_mbcnt_lo_u32_b32 v4, -1, 0
	v_lshl_add_u64 v[72:73], s[14:15], 0, v[48:49]
	v_writelane_b32 v255, s3, 9
	v_cmp_ne_u32_e64 s[2:3], 0, v92
	s_mov_b32 s0, s16
	s_mul_i32 s74, s16, 0x48
	v_writelane_b32 v255, s2, 10
	v_lshl_add_u32 v86, v46, 8, v50
	v_and_b32_e32 v87, 0xffffff00, v0
	v_writelane_b32 v255, s3, 11
	v_cmp_lt_u32_e64 s[2:3], s66, v11
	v_add_u32_e32 v1, 0x200, v0
	v_lshl_add_u32 v94, v21, 9, v0
	v_writelane_b32 v254, s2, 54
	v_and_b32_e32 v96, -2, v18
	s_lshl_b32 s92, s33, 6
	v_writelane_b32 v254, s3, 55
	v_cmp_lt_u32_e64 s[2:3], 1, v16
	v_readlane_b32 s4, v254, 8
	v_lshlrev_b32_e32 v97, 7, v6
	v_writelane_b32 v255, s2, 12
	v_lshlrev_b32_e32 v98, 5, v6
	v_mul_u32_u24_e32 v99, 48, v6
	v_writelane_b32 v255, s3, 13
	v_cmp_eq_u32_e64 s[2:3], 0, v22
	v_lshlrev_b32_e32 v100, 6, v6
	v_mul_u32_u24_e32 v101, 0x50, v6
	v_writelane_b32 v255, s2, 14
	v_mul_u32_u24_e32 v102, 0x60, v6
	v_mul_u32_u24_e32 v103, 0x70, v6
	v_writelane_b32 v255, s3, 15
	v_cmp_ne_u32_e64 s[2:3], v12, v21
	v_add_u32_e32 v104, v20, v8
	s_mov_b32 s94, 0x300000
	v_writelane_b32 v255, s2, 16
	s_movk_i32 s96, 0x3dff
	s_movk_i32 s97, 0x2000
	v_writelane_b32 v255, s3, 17
	v_cmp_lt_u32_e64 s[2:3], 1, v17
	s_movk_i32 s64, 0x7fff
	s_mov_b32 s65, 0x7060302
	v_writelane_b32 v255, s2, 18
	s_mov_b32 s28, 0xfe5163ab
	s_mov_b32 s29, 0x3c439041
	v_writelane_b32 v255, s3, 19
	v_cmp_eq_u32_e64 s[2:3], 0, v2
	s_mov_b32 s63, 0xdb629599
	v_add_u32_e32 v107, 0x10000, v83
	v_writelane_b32 v255, s2, 20
	v_mbcnt_hi_u32_b32 v108, -1, v4
	v_add_u32_e32 v109, 0x10800, v83
	v_writelane_b32 v255, s3, 21
	v_cmp_ne_u32_e64 s[2:3], v10, v23
	v_mov_b32_e32 v110, 0x3c0881c4
	v_mov_b32_e32 v111, 0xbab64f3b
	v_writelane_b32 v255, s2, 22
	v_not_b32_e32 v112, 63
	v_not_b32_e32 v113, 31
	v_lshl_add_u32 v74, v19, 9, v0
	v_lshl_add_u32 v76, v23, 9, v0
	v_lshlrev_b32_e32 v78, 2, v46
	s_mov_b32 s20, 0xf534ddc0
	s_mov_b32 s21, 0xfc2757d1
	s_mov_b32 s24, 0x4e441529
	s_mov_b32 s25, 0xa2f9836e
	s_mov_b32 s34, 0x3fc90fda
	s_mov_b32 s35, 0xbfc90fda
	s_movk_i32 s36, 0x2800
	s_movk_i32 s37, 0x104
	s_mov_b32 s38, 0xbfb8aa3b
	s_mov_b32 s39, 0x42ce8ed0
	s_mov_b32 s95, 0xc2b17218
	s_mov_b32 s73, 0
	v_cmp_gt_i32_e64 s[58:59], s60, v0
	v_cmp_gt_i32_e64 s[30:31], s61, v0
	v_cmp_gt_i32_e64 s[42:43], 64, v0
	v_cmp_gt_i32_e64 s[68:69], s62, v0
	v_cmp_eq_u32_e64 s[70:71], 0, v200
	v_cmp_lt_u32_e64 s[40:41], s66, v9
	v_writelane_b32 v255, s3, 23
	v_readlane_b32 s10, v254, 14
	v_readlane_b32 s11, v254, 15
	s_mov_b64 s[84:85], 0x800
	v_readlane_b32 s5, v254, 9
	v_readlane_b32 s6, v254, 10
	v_readlane_b32 s7, v254, 11
	v_readlane_b32 s8, v254, 12
	v_readlane_b32 s9, v254, 13
	v_readlane_b32 s12, v254, 16
	v_readlane_b32 s13, v254, 17
	v_readlane_b32 s14, v254, 18
	v_readlane_b32 s15, v254, 19
	v_readlane_b32 s16, v254, 20
	v_readlane_b32 s17, v254, 21
	v_readlane_b32 s18, v254, 22
	v_readlane_b32 s19, v254, 23
	s_branch .LBB0_67
